# v28 + LN row-statistics all-reduce by DPP adds and one readlane instead of six ds_bpermute round trips
# baseline (speedup 1.0000x reference)
.Lln1_nopf:
	v_mov_b32_e32 v134, v136
	v_mov_b32_e32 v135, v144
	v_mov_b32_e32 v148, v137
	v_mov_b32_e32 v149, v145
	v_pk_add_f32 v[134:135], v[134:135], v[148:149]
	v_mov_b32_e32 v148, v140
	v_mov_b32_e32 v149, v146
	v_mov_b32_e32 v150, v141
	v_mov_b32_e32 v151, v147
	v_pk_add_f32 v[148:149], v[148:149], v[150:151]
	v_mov_b32_e32 v150, v138
	v_pk_add_f32 v[134:135], v[134:135], v[148:149]
	v_mov_b32_e32 v148, v139
	v_mov_b32_e32 v149, v142
	v_mov_b32_e32 v151, v143
	v_pk_add_f32 v[148:149], v[148:149], v[150:151]
	v_add_f32_e32 v65, 0, v135
	v_pk_add_f32 v[148:149], v[148:149], v[148:149] op_sel_hi:[0,1]
	v_add_f32_e32 v135, v134, v65
	v_add_f32_e32 v151, v86, v87
	v_add_f32_e32 v153, v98, v99
	v_mov_b32_e32 v150, v88
	v_mov_b32_e32 v152, v89
	v_mov_b32_e32 v148, v100
	v_mov_b32_e32 v134, v101
	v_pk_add_f32 v[150:151], v[150:151], v[152:153]
	v_pk_add_f32 v[134:135], v[148:149], v[134:135]
	v_mov_b32_e32 v148, v79
	v_pk_add_f32 v[134:135], v[150:151], v[134:135]
	v_mov_b32_e32 v149, v82
	v_mov_b32_e32 v150, v78
	v_mov_b32_e32 v151, v83
	v_pk_add_f32 v[148:149], v[148:149], v[150:151]
	v_pk_add_f32 v[134:135], v[134:135], v[134:135] op_sel_hi:[0,1]
	v_pk_add_f32 v[148:149], v[148:149], v[148:149] op_sel_hi:[0,1]
	v_add_f32_e32 v151, v80, v81
	v_add_f32_e32 v153, v84, v85
	v_mov_b32_e32 v150, v74
	v_mov_b32_e32 v152, v75
	v_mov_b32_e32 v148, v76
	v_mov_b32_e32 v134, v77
	v_pk_add_f32 v[150:151], v[150:151], v[152:153]
	v_pk_add_f32 v[134:135], v[148:149], v[134:135]
	s_nop 0
	v_pk_add_f32 v[134:135], v[150:151], v[134:135]
	s_nop 0
	v_add_f32_e32 v65, v134, v135
	s_nop 1
	v_add_f32_dpp v65, v65, v65 quad_perm:[1,0,3,2] row_mask:0xf bank_mask:0xf
	s_nop 1
	v_add_f32_dpp v65, v65, v65 quad_perm:[2,3,0,1] row_mask:0xf bank_mask:0xf
	s_nop 1
	v_add_f32_dpp v65, v65, v65 row_half_mirror row_mask:0xf bank_mask:0xf
	s_nop 1
	v_add_f32_dpp v65, v65, v65 row_mirror row_mask:0xf bank_mask:0xf
	s_nop 1
	v_add_f32_dpp v65, v65, v65 row_bcast:15 row_mask:0xa bank_mask:0xf
	s_nop 1
	v_add_f32_dpp v65, v65, v65 row_bcast:31 row_mask:0xc bank_mask:0xf
	s_nop 1
	v_readlane_b32 vcc_lo, v65, 63
	s_nop 1
	v_mov_b32_e32 v65, vcc_lo
	v_fmamk_f32 v147, v65, 0xba000000, v147
	v_fmamk_f32 v149, v65, 0xba000000, v145
	v_fmamk_f32 v146, v65, 0xba000000, v146
	v_fmamk_f32 v148, v65, 0xba000000, v144
	v_mul_f32_e32 v134, v149, v149
	v_mul_f32_e32 v135, v147, v147
	v_fmac_f32_e32 v134, v148, v148
	v_fmac_f32_e32 v135, v146, v146
	v_fmamk_f32 v145, v65, 0xba000000, v141
	v_fmamk_f32 v151, v65, 0xba000000, v137
	v_add_f32_e32 v134, v134, v135
	v_fmamk_f32 v144, v65, 0xba000000, v140
	v_fmamk_f32 v150, v65, 0xba000000, v136
	v_mul_f32_e32 v135, v151, v151
	v_mul_f32_e32 v136, v145, v145
	v_fmac_f32_e32 v135, v150, v150
	v_fmac_f32_e32 v136, v144, v144
	v_add_f32_e32 v135, v135, v136
	v_add_f32_e32 v140, v134, v135
	v_fmamk_f32 v135, v65, 0xba000000, v143
	v_fmamk_f32 v137, v65, 0xba000000, v139
	v_fmamk_f32 v134, v65, 0xba000000, v142
	v_fmamk_f32 v136, v65, 0xba000000, v138
	v_mul_f32_e32 v138, v137, v137
	v_mul_f32_e32 v139, v135, v135
	v_fmac_f32_e32 v138, v136, v136
	v_fmac_f32_e32 v139, v134, v134
	v_add_f32_e32 v138, v138, v139
	v_fmamk_f32 v139, v65, 0xba000000, v99
	v_fmamk_f32 v141, v65, 0xba000000, v87
	v_add_f32_e32 v142, v138, v140
	v_fmamk_f32 v138, v65, 0xba000000, v98
	v_fmamk_f32 v140, v65, 0xba000000, v86
	v_mul_f32_e32 v86, v141, v141
	v_mul_f32_e32 v87, v139, v139
	v_fmac_f32_e32 v86, v140, v140
	v_fmac_f32_e32 v87, v138, v138
	v_add_f32_e32 v86, v86, v87
	v_fmamk_f32 v87, v65, 0xba000000, v101
	v_fmamk_f32 v89, v65, 0xba000000, v89
	v_add_f32_e32 v98, v86, v142
	v_fmamk_f32 v86, v65, 0xba000000, v100
	v_fmamk_f32 v88, v65, 0xba000000, v88
	v_mul_f32_e32 v99, v89, v89
	v_mul_f32_e32 v100, v87, v87
	v_fmac_f32_e32 v99, v88, v88
	v_fmac_f32_e32 v100, v86, v86
	v_add_f32_e32 v99, v99, v100
	v_add_f32_e32 v100, v99, v98
	v_fmamk_f32 v83, v65, 0xba000000, v83
	v_fmamk_f32 v99, v65, 0xba000000, v79
	v_fmamk_f32 v82, v65, 0xba000000, v82
	v_fmamk_f32 v98, v65, 0xba000000, v78
	v_mul_f32_e32 v78, v99, v99
	v_mul_f32_e32 v79, v83, v83
	v_fmac_f32_e32 v78, v98, v98
	v_fmac_f32_e32 v79, v82, v82
	v_add_f32_e32 v78, v78, v79
	v_fmamk_f32 v79, v65, 0xba000000, v85
	v_fmamk_f32 v81, v65, 0xba000000, v81
	v_add_f32_e32 v100, v78, v100
	v_fmamk_f32 v78, v65, 0xba000000, v84
	v_fmamk_f32 v80, v65, 0xba000000, v80
	v_mul_f32_e32 v84, v81, v81
	v_mul_f32_e32 v85, v79, v79
	v_fmac_f32_e32 v84, v80, v80
	v_fmac_f32_e32 v85, v78, v78
	v_add_f32_e32 v84, v84, v85
	v_fmamk_f32 v77, v65, 0xba000000, v77
	v_fmamk_f32 v75, v65, 0xba000000, v75
	v_add_f32_e32 v84, v84, v100
	v_fmamk_f32 v76, v65, 0xba000000, v76
	v_fmac_f32_e32 v74, 0xba000000, v65
	v_mul_f32_e32 v85, v75, v75
	v_mul_f32_e32 v100, v77, v77
	v_fmac_f32_e32 v85, v74, v74
	v_fmac_f32_e32 v100, v76, v76
	v_add_f32_e32 v85, v85, v100
	v_add_f32_e32 v84, v85, v84
	s_nop 1
	v_add_f32_dpp v84, v84, v84 quad_perm:[1,0,3,2] row_mask:0xf bank_mask:0xf
	s_nop 1
	v_add_f32_dpp v84, v84, v84 quad_perm:[2,3,0,1] row_mask:0xf bank_mask:0xf
	s_nop 1
	v_add_f32_dpp v84, v84, v84 row_half_mirror row_mask:0xf bank_mask:0xf
	s_nop 1
	v_add_f32_dpp v84, v84, v84 row_mirror row_mask:0xf bank_mask:0xf
	s_nop 1
	v_add_f32_dpp v84, v84, v84 row_bcast:15 row_mask:0xa bank_mask:0xf
	s_nop 1
	v_add_f32_dpp v84, v84, v84 row_bcast:31 row_mask:0xc bank_mask:0xf
	s_nop 1
	v_readlane_b32 vcc_lo, v84, 63
	s_nop 1
	v_mov_b32_e32 v84, vcc_lo
	v_fmamk_f32 v84, v84, 0x3a000000, v220
	v_mul_f32_e32 v85, 0x4f800000, v84
	v_cmp_gt_f32_e32 vcc, s77, v84
	s_nop 1
	v_cndmask_b32_e32 v84, v84, v85, vcc
	v_sqrt_f32_e32 v85, v84
	s_nop 0
	v_add_u32_e32 v100, -1, v85
	v_fma_f32 v101, -v100, v85, v84
	v_cmp_ge_f32_e64 s[38:39], 0, v101
	v_add_u32_e32 v101, 1, v85
	s_nop 0
	v_cndmask_b32_e64 v100, v85, v100, s[38:39]
	v_fma_f32 v85, -v101, v85, v84
	v_cmp_lt_f32_e64 s[38:39], 0, v85
	s_nop 1
	v_cndmask_b32_e64 v85, v100, v101, s[38:39]
	v_mul_f32_e32 v100, 0x37800000, v85
	v_cndmask_b32_e32 v85, v85, v100, vcc
	v_cmp_class_f32_e32 vcc, v84, v219
	s_nop 1
	v_cndmask_b32_e32 v84, v85, v84, vcc
	v_div_scale_f32 v85, s[20:21], v84, v84, 1.0
	v_rcp_f32_e32 v100, v85
	s_nop 0
	v_fma_f32 v101, -v85, v100, 1.0
	v_fmac_f32_e32 v100, v101, v100
	v_div_scale_f32 v101, vcc, 1.0, v84, 1.0
	v_mul_f32_e32 v142, v101, v100
	v_fma_f32 v143, -v85, v142, v101
	v_fmac_f32_e32 v142, v143, v100
	v_fma_f32 v85, -v85, v142, v101
	v_div_fmas_f32 v85, v85, v100, v142
	v_div_fixup_f32 v84, v85, v84, 1.0
	s_and_saveexec_b64 s[20:21], s[36:37]
	s_cbranch_execz .LBB0_980
	v_mul_f32_e32 v100, 0x3a000000, v65
	v_mov_b32_e32 v101, v84
	global_store_dwordx2 v64, v[100:101], s[6:7]
	s_branch .LBB0_980

.Lln2_nopf:
	v_mov_b32_e32 v84, v150
	v_mov_b32_e32 v85, v158
	v_mov_b32_e32 v146, v151
	v_mov_b32_e32 v147, v159
	v_pk_add_f32 v[84:85], v[84:85], v[146:147]
	v_mov_b32_e32 v146, v154
	v_mov_b32_e32 v147, v160
	v_mov_b32_e32 v162, v155
	v_mov_b32_e32 v163, v161
	v_pk_add_f32 v[146:147], v[146:147], v[162:163]
	v_mov_b32_e32 v162, v152
	v_pk_add_f32 v[84:85], v[84:85], v[146:147]
	v_mov_b32_e32 v146, v153
	v_mov_b32_e32 v147, v156
	v_mov_b32_e32 v163, v157
	v_pk_add_f32 v[146:147], v[146:147], v[162:163]
	v_add_f32_e32 v65, 0, v85
	v_pk_add_f32 v[146:147], v[146:147], v[146:147] op_sel_hi:[0,1]
	v_add_f32_e32 v85, v84, v65
	v_add_f32_e32 v163, v96, v97
	v_add_f32_e32 v165, v100, v101
	v_mov_b32_e32 v162, v98
	v_mov_b32_e32 v164, v99
	v_mov_b32_e32 v146, v148
	v_mov_b32_e32 v84, v149
	v_pk_add_f32 v[162:163], v[162:163], v[164:165]
	v_pk_add_f32 v[84:85], v[146:147], v[84:85]
	v_mov_b32_e32 v146, v87
	v_pk_add_f32 v[84:85], v[162:163], v[84:85]
	v_mov_b32_e32 v147, v92
	v_mov_b32_e32 v162, v86
	v_mov_b32_e32 v163, v93
	v_pk_add_f32 v[146:147], v[146:147], v[162:163]
	v_pk_add_f32 v[84:85], v[84:85], v[84:85] op_sel_hi:[0,1]
	v_pk_add_f32 v[146:147], v[146:147], v[146:147] op_sel_hi:[0,1]
	v_add_f32_e32 v163, v88, v89
	v_add_f32_e32 v165, v94, v95
	v_mov_b32_e32 v162, v90
	v_mov_b32_e32 v164, v91
	v_mov_b32_e32 v146, v82
	v_mov_b32_e32 v84, v83
	v_pk_add_f32 v[162:163], v[162:163], v[164:165]
	v_pk_add_f32 v[84:85], v[146:147], v[84:85]
	s_nop 0
	v_pk_add_f32 v[84:85], v[162:163], v[84:85]
	s_nop 0
	v_add_f32_e32 v65, v84, v85
	s_nop 1
	v_add_f32_dpp v65, v65, v65 quad_perm:[1,0,3,2] row_mask:0xf bank_mask:0xf
	s_nop 1
	v_add_f32_dpp v65, v65, v65 quad_perm:[2,3,0,1] row_mask:0xf bank_mask:0xf
	s_nop 1
	v_add_f32_dpp v65, v65, v65 row_half_mirror row_mask:0xf bank_mask:0xf
	s_nop 1
	v_add_f32_dpp v65, v65, v65 row_mirror row_mask:0xf bank_mask:0xf
	s_nop 1
	v_add_f32_dpp v65, v65, v65 row_bcast:15 row_mask:0xa bank_mask:0xf
	s_nop 1
	v_add_f32_dpp v65, v65, v65 row_bcast:31 row_mask:0xc bank_mask:0xf
	s_nop 1
	v_readlane_b32 vcc_lo, v65, 63
	s_nop 1
	v_mov_b32_e32 v65, vcc_lo
	v_fmamk_f32 v85, v65, 0xba000000, v161
	v_fmamk_f32 v177, v65, 0xba000000, v159
	v_fmamk_f32 v84, v65, 0xba000000, v160
	v_fmamk_f32 v176, v65, 0xba000000, v158
	v_mul_f32_e32 v146, v177, v177
	v_mul_f32_e32 v147, v85, v85
	v_fmac_f32_e32 v146, v176, v176
	v_fmac_f32_e32 v147, v84, v84
	v_fmamk_f32 v161, v65, 0xba000000, v155
	v_fmamk_f32 v175, v65, 0xba000000, v151
	v_add_f32_e32 v146, v146, v147
	v_fmamk_f32 v160, v65, 0xba000000, v154
	v_fmamk_f32 v174, v65, 0xba000000, v150
	v_mul_f32_e32 v147, v175, v175
	v_mul_f32_e32 v150, v161, v161
	v_fmac_f32_e32 v147, v174, v174
	v_fmac_f32_e32 v150, v160, v160
	v_add_f32_e32 v147, v147, v150
	v_fmamk_f32 v157, v65, 0xba000000, v157
	v_fmamk_f32 v159, v65, 0xba000000, v153
	v_add_f32_e32 v146, v146, v147
	v_fmamk_f32 v156, v65, 0xba000000, v156
	v_fmamk_f32 v158, v65, 0xba000000, v152
	v_mul_f32_e32 v147, v159, v159
	v_mul_f32_e32 v150, v157, v157
	v_fmamk_f32 v153, v65, 0xba000000, v101
	v_fmamk_f32 v155, v65, 0xba000000, v97
	v_fmac_f32_e32 v147, v158, v158
	v_fmac_f32_e32 v150, v156, v156
	v_fmamk_f32 v152, v65, 0xba000000, v100
	v_fmamk_f32 v154, v65, 0xba000000, v96
	v_mul_f32_e32 v96, v155, v155
	v_mul_f32_e32 v97, v153, v153
	v_add_f32_e32 v147, v147, v150
	v_fmac_f32_e32 v96, v154, v154
	v_fmac_f32_e32 v97, v152, v152
	v_add_f32_e32 v146, v147, v146
	v_add_f32_e32 v96, v96, v97
	v_fmamk_f32 v147, v65, 0xba000000, v149
	v_fmamk_f32 v149, v65, 0xba000000, v99
	v_add_f32_e32 v96, v96, v146
	v_fmamk_f32 v146, v65, 0xba000000, v148
	v_fmamk_f32 v148, v65, 0xba000000, v98
	v_mul_f32_e32 v97, v149, v149
	v_mul_f32_e32 v98, v147, v147
	v_fmac_f32_e32 v97, v148, v148
	v_fmac_f32_e32 v98, v146, v146
	v_fmamk_f32 v99, v65, 0xba000000, v93
	v_fmamk_f32 v101, v65, 0xba000000, v87
	v_add_f32_e32 v97, v97, v98
	v_fmamk_f32 v98, v65, 0xba000000, v92
	v_fmamk_f32 v100, v65, 0xba000000, v86
	v_mul_f32_e32 v86, v101, v101
	v_mul_f32_e32 v87, v99, v99
	v_fmac_f32_e32 v86, v100, v100
	v_fmac_f32_e32 v87, v98, v98
	v_add_f32_e32 v96, v97, v96
	v_add_f32_e32 v86, v86, v87
	v_fmamk_f32 v95, v65, 0xba000000, v95
	v_fmamk_f32 v97, v65, 0xba000000, v89
	v_add_f32_e32 v86, v86, v96
	v_fmamk_f32 v94, v65, 0xba000000, v94
	v_fmamk_f32 v96, v65, 0xba000000, v88
	v_mul_f32_e32 v87, v97, v97
	v_mul_f32_e32 v88, v95, v95
	v_fmamk_f32 v93, v65, 0xba000000, v83
	v_fmamk_f32 v91, v65, 0xba000000, v91
	v_fmac_f32_e32 v87, v96, v96
	v_fmac_f32_e32 v88, v94, v94
	v_fmamk_f32 v92, v65, 0xba000000, v82
	v_fmac_f32_e32 v90, 0xba000000, v65
	v_mul_f32_e32 v82, v91, v91
	v_mul_f32_e32 v83, v93, v93
	v_add_f32_e32 v87, v87, v88
	v_fmac_f32_e32 v82, v90, v90
	v_fmac_f32_e32 v83, v92, v92
	v_add_f32_e32 v86, v87, v86
	v_add_f32_e32 v82, v82, v83
	v_add_f32_e32 v82, v82, v86
	s_nop 1
	v_add_f32_dpp v82, v82, v82 quad_perm:[1,0,3,2] row_mask:0xf bank_mask:0xf
	s_nop 1
	v_add_f32_dpp v82, v82, v82 quad_perm:[2,3,0,1] row_mask:0xf bank_mask:0xf
	s_nop 1
	v_add_f32_dpp v82, v82, v82 row_half_mirror row_mask:0xf bank_mask:0xf
	s_nop 1
	v_add_f32_dpp v82, v82, v82 row_mirror row_mask:0xf bank_mask:0xf
	s_nop 1
	v_add_f32_dpp v82, v82, v82 row_bcast:15 row_mask:0xa bank_mask:0xf
	s_nop 1
	v_add_f32_dpp v82, v82, v82 row_bcast:31 row_mask:0xc bank_mask:0xf
	s_nop 1
	v_readlane_b32 vcc_lo, v82, 63
	s_nop 1
	v_mov_b32_e32 v82, vcc_lo
	v_fmamk_f32 v82, v82, 0x3a000000, v220
	v_mul_f32_e32 v83, 0x4f800000, v82
	v_cmp_gt_f32_e32 vcc, s77, v82
	s_nop 1
	v_cndmask_b32_e32 v82, v82, v83, vcc
	v_sqrt_f32_e32 v83, v82
	s_nop 0
	v_add_u32_e32 v86, -1, v83
	v_fma_f32 v87, -v86, v83, v82
	v_cmp_ge_f32_e64 s[38:39], 0, v87
	v_add_u32_e32 v87, 1, v83
	s_nop 0
	v_cndmask_b32_e64 v86, v83, v86, s[38:39]
	v_fma_f32 v83, -v87, v83, v82
	v_cmp_lt_f32_e64 s[38:39], 0, v83
	s_nop 1
	v_cndmask_b32_e64 v83, v86, v87, s[38:39]
	v_mul_f32_e32 v86, 0x37800000, v83
	v_cndmask_b32_e32 v83, v83, v86, vcc
	v_cmp_class_f32_e32 vcc, v82, v219
	s_nop 1
	v_cndmask_b32_e32 v82, v83, v82, vcc
	v_div_scale_f32 v83, s[38:39], v82, v82, 1.0
	v_rcp_f32_e32 v86, v83
	s_nop 0
	v_fma_f32 v87, -v83, v86, 1.0
	v_fmac_f32_e32 v86, v87, v86
	v_div_scale_f32 v87, vcc, 1.0, v82, 1.0
	v_mul_f32_e32 v88, v87, v86
	v_fma_f32 v89, -v83, v88, v87
	v_fmac_f32_e32 v88, v89, v86
	v_fma_f32 v83, -v83, v88, v87
	v_div_fmas_f32 v83, v83, v86, v88
	v_div_fixup_f32 v150, v83, v82, 1.0
	s_and_saveexec_b64 s[38:39], s[36:37]
	s_cbranch_execz .LBB0_1408
	v_mul_f32_e32 v82, 0x3a000000, v65
	v_mov_b32_e32 v83, v150
	global_store_dwordx2 v64, v[82:83], s[10:11]
